# phase 2: static s_setprio 1 for gdn_prep items (critical 3-round chain), S5 pipeline items stay at 0
# speedup vs baseline: 1.0031x; 1.0031x over previous
.LBB0_212:
	s_setprio 1
	s_and_b64 vcc, exec, s[0:1]
	s_cbranch_vccz .LBB0_446
	s_add_i32 s64, s36, 0xffffff00
	s_and_b32 s15, s36, 31
	s_lshr_b32 s14, s64, 7
	s_bfe_u32 s16, s36, 0x20005
	s_lshl_b32 s18, s15, 6
	s_lshl_b32 s19, s14, 11
	s_barrier
	s_bfe_u32 s68, s64, 0x20005
	s_lshr_b32 s69, s64, 7
	s_and_b32 s70, s64, 31
	v_readlane_b32 s72, v251, 28
	v_readlane_b32 s73, v251, 29
	s_lshl_b32 s71, s68, 9
	s_mul_i32 s74, s69, 0xa00000
	s_lshl_b32 s75, s68, 8
	s_add_u32 s74, s74, s75
	s_add_u32 s74, s74, 0x400
	s_add_u32 s76, s28, s74
	s_addc_u32 s77, s29, 0
	s_add_u32 s72, s72, s71
	s_addc_u32 s73, s73, 0
	s_lshl_b32 s78, s70, 6
	s_sub_u32 s78, s78, 3
	v_lshrrev_b32_e32 v64, 2, v162
	v_and_b32_e32 v65, 3, v162
	v_add_u32_e32 v66, s78, v64
	v_mov_b32_e32 v67, v66
	v_max_i32_e32 v67, 0, v67
	v_mul_u32_u24_e32 v67, 0x1400, v67
	v_lshl_add_u32 v248, v65, 6, v67
	v_add_u32_e32 v67, 1, v66
	v_max_i32_e32 v67, 0, v67
	v_mul_u32_u24_e32 v67, 0x1400, v67
	v_lshl_add_u32 v249, v65, 6, v67
	v_add_u32_e32 v67, 2, v66
	v_max_i32_e32 v67, 0, v67
	v_mul_u32_u24_e32 v67, 0x1400, v67
	v_lshl_add_u32 v253, v65, 6, v67
	v_add_u32_e32 v67, 3, v66
	v_max_i32_e32 v67, 0, v67
	v_mul_u32_u24_e32 v67, 0x1400, v67
	v_lshl_add_u32 v254, v65, 6, v67
	v_lshrrev_b32_e32 v66, 5, v162
	v_and_b32_e32 v67, 31, v162
	v_lshlrev_b32_e32 v68, 11, v66
	v_lshl_add_u32 v68, v67, 4, v68
	v_mul_u32_u24_e32 v69, 0x240, v66
	v_lshrrev_b32_e32 v70, 3, v67
	v_mul_u32_u24_e32 v70, 0x90, v70
	v_and_b32_e32 v71, 7, v67
	v_lshl_add_u32 v70, v71, 4, v70
	v_add_u32_e32 v69, v69, v70
	v_add_u32_e32 v22, 0xc400, v69
	v_cmp_gt_u32_e32 vcc, 0x80, v162
	v_mov_b32_e32 v71, 0x4000
	v_mov_b32_e32 v70, 0x1200
	s_nop 1
	v_cndmask_b32_e32 v71, 0, v71, vcc
	v_cndmask_b32_e32 v70, 0, v70, vcc
	v_add_u32_e32 v69, v68, v71
	v_add_u32_e32 v23, v22, v70
	global_load_dwordx4 v[56:59], v68, s[72:73]
	global_load_dwordx4 v[60:63], v69, s[72:73]
	global_load_dwordx4 v[28:31], v248, s[76:77] offset:0
	global_load_dwordx4 v[32:35], v249, s[76:77] offset:0
	global_load_dwordx4 v[36:39], v253, s[76:77] offset:0
	global_load_dwordx4 v[40:43], v254, s[76:77] offset:0
	global_load_dwordx4 v[44:47], v248, s[76:77] offset:16
	global_load_dwordx4 v[52:55], v249, s[76:77] offset:16
	s_and_saveexec_b64 s[0:1], s[10:11]
	s_cbranch_execz .LBB0_215
	s_or_b32 s17, s18, s19
	v_or_b32_e32 v0, s17, v162
	v_readlane_b32 s68, v251, 8
	v_lshlrev_b32_e32 v0, 3, v0
	v_readlane_b32 s69, v251, 9
	v_readlane_b32 s70, v251, 10
	v_readlane_b32 s71, v251, 11
	v_readlane_b32 s72, v251, 12
	v_readlane_b32 s73, v251, 13
	v_readlane_b32 s74, v251, 14
	v_readlane_b32 s75, v251, 15
	v_readlane_b32 s76, v251, 16
	v_readlane_b32 s77, v251, 17
	v_readlane_b32 s78, v251, 18
	v_readlane_b32 s79, v251, 19
	v_readlane_b32 s80, v251, 20
	v_readlane_b32 s81, v251, 21
	v_readlane_b32 s82, v251, 22
	v_readlane_b32 s83, v251, 23
	v_lshl_add_u64 v[2:3], v[0:1], 2, s[74:75]
	v_readlane_b32 s68, v251, 24
	s_lshl_b32 s8, s16, 2
	v_readlane_b32 s69, v251, 25
	v_readlane_b32 s70, v251, 26
	v_readlane_b32 s71, v251, 27
	v_readlane_b32 s72, v251, 28
	v_readlane_b32 s73, v251, 29
	v_readlane_b32 s74, v251, 30
	v_readlane_b32 s75, v251, 31
	v_lshl_add_u64 v[2:3], v[2:3], 0, s[8:9]
	v_readlane_b32 s76, v251, 32
	v_readlane_b32 s77, v251, 33
	v_readlane_b32 s78, v251, 34
	v_readlane_b32 s79, v251, 35
	s_mov_b64 s[68:69], s[72:73]
	global_load_dword v0, v[2:3], off
	s_mov_b64 s[70:71], s[74:75]
	global_load_dword v2, v[2:3], off offset:16
	v_mov_b32_e32 v3, s8
	s_mov_b64 s[72:73], s[76:77]
	global_load_dword v8, v3, s[72:73]
	s_mov_b32 s8, 0xbfb8aa3b
	s_mov_b32 s17, 0xb2a5705f
	global_load_dword v3, v3, s[70:71]
	v_readlane_b32 s12, v252, 34
	v_readlane_b32 s13, v252, 35
	v_readlane_b32 s80, v251, 36
	v_readlane_b32 s81, v251, 37
	v_readlane_b32 s82, v251, 38
	v_readlane_b32 s83, v251, 39
	s_mov_b64 s[74:75], s[78:79]
	s_waitcnt vmcnt(3)
	v_mul_f32_e32 v0, 0xbfb8aa3b, v0
	v_exp_f32_e32 v0, v0
	s_waitcnt vmcnt(1)
	v_add_f32_e32 v2, v2, v8
	v_mul_f32_e64 v8, |v2|, s8
	v_fma_f32 v9, |v2|, s8, -v8
	v_rndne_f32_e32 v11, v8
	v_fma_f32 v9, |v2|, s17, v9
	v_sub_f32_e32 v8, v8, v11
	v_add_f32_e32 v8, v8, v9
	v_exp_f32_e32 v8, v8
	v_cvt_i32_f32_e32 v9, v11
	s_mov_b32 s17, 0x42ce8ed0
	v_cmp_ngt_f32_e64 vcc, |v2|, s17
	s_mov_b32 s17, 0xc2b17218
	v_ldexp_f32 v8, v8, v9
	v_cndmask_b32_e32 v8, 0, v8, vcc
	v_cmp_nlt_f32_e64 vcc, |v2|, s17
	v_max_f32_e32 v10, 0, v2
	s_mov_b32 s17, 0x3f2aaaab
	v_cndmask_b32_e32 v2, v207, v8, vcc
	v_add_f32_e32 v11, 1.0, v2
	v_add_f32_e32 v8, -1.0, v11
	v_sub_f32_e32 v9, v8, v11
	v_add_f32_e32 v9, 1.0, v9
	v_sub_f32_e32 v8, v2, v8
	v_add_f32_e32 v12, v8, v9
	v_frexp_mant_f32_e32 v8, v11
	v_cmp_gt_f32_e32 vcc, s17, v8
	v_cvt_f64_f32_e32 v[8:9], v11
	v_frexp_exp_i32_f64_e32 v8, v[8:9]
	v_subbrev_co_u32_e32 v8, vcc, 0, v8, vcc
	v_sub_u32_e32 v9, 0, v8
	v_ldexp_f32 v11, v11, v9
	v_ldexp_f32 v9, v12, v9
	v_add_f32_e32 v12, -1.0, v11
	v_add_f32_e32 v13, 1.0, v12
	v_sub_f32_e32 v13, v11, v13
	v_add_f32_e32 v13, v9, v13
	v_add_f32_e32 v14, v12, v13
	v_sub_f32_e32 v12, v12, v14
	v_add_f32_e32 v12, v13, v12
	v_add_f32_e32 v13, 1.0, v11
	v_add_f32_e32 v15, -1.0, v13
	v_sub_f32_e32 v11, v11, v15
	v_add_f32_e32 v9, v9, v11
	v_add_f32_e32 v11, v13, v9
	v_sub_f32_e32 v13, v13, v11
	v_add_f32_e32 v9, v9, v13
	v_rcp_f32_e32 v13, v11
	v_cvt_f32_i32_e32 v8, v8
	s_mov_b32 s17, 0x3f317218
	v_cmp_neq_f32_e32 vcc, s37, v2
	v_mul_f32_e32 v15, v14, v13
	v_mul_f32_e32 v16, v11, v15
	v_fma_f32 v17, v15, v11, -v16
	v_fmac_f32_e32 v17, v15, v9
	v_add_f32_e32 v18, v16, v17
	v_sub_f32_e32 v19, v14, v18
	v_sub_f32_e32 v14, v14, v19
	v_sub_f32_e32 v16, v18, v16
	v_sub_f32_e32 v14, v14, v18
	v_add_f32_e32 v12, v12, v14
	v_sub_f32_e32 v14, v16, v17
	v_add_f32_e32 v12, v14, v12
	v_add_f32_e32 v14, v19, v12
	v_mul_f32_e32 v16, v13, v14
	v_mul_f32_e32 v17, v11, v16
	v_fma_f32 v11, v16, v11, -v17
	v_fmac_f32_e32 v11, v16, v9
	v_sub_f32_e32 v9, v19, v14
	v_add_f32_e32 v9, v12, v9
	v_add_f32_e32 v12, v17, v11
	v_sub_f32_e32 v18, v14, v12
	v_sub_f32_e32 v14, v14, v18
	v_sub_f32_e32 v17, v12, v17
	v_sub_f32_e32 v12, v14, v12
	v_add_f32_e32 v9, v9, v12
	v_sub_f32_e32 v11, v17, v11
	v_add_f32_e32 v9, v11, v9
	v_add_f32_e32 v11, v15, v16
	v_add_f32_e32 v9, v18, v9
	v_sub_f32_e32 v12, v11, v15
	v_mul_f32_e32 v9, v13, v9
	v_sub_f32_e32 v12, v16, v12
	v_add_f32_e32 v9, v12, v9
	v_mul_f32_e32 v15, 0x3f317218, v8
	v_add_f32_e32 v12, v11, v9
	v_fma_f32 v16, v8, s17, -v15
	v_mul_f32_e32 v13, v12, v12
	v_fmac_f32_e32 v16, 0xb102e308, v8
	v_sub_f32_e32 v8, v12, v11
	v_fmamk_f32 v14, v13, 0x3e9b6dac, v197
	v_sub_f32_e32 v8, v9, v8
	v_add_f32_e32 v9, v15, v16
	v_fmaak_f32 v14, v13, v14, 0x3f2aaada
	v_sub_f32_e32 v11, v9, v15
	v_ldexp_f32 v15, v12, 1
	v_mul_f32_e32 v12, v12, v13
	v_mul_f32_e32 v12, v12, v14
	v_add_f32_e32 v13, v15, v12
	v_sub_f32_e32 v14, v13, v15
	v_ldexp_f32 v8, v8, 1
	v_sub_f32_e32 v12, v12, v14
	v_add_f32_e32 v8, v8, v12
	v_add_f32_e32 v12, v13, v8
	v_sub_f32_e32 v13, v12, v13
	v_sub_f32_e32 v8, v8, v13
	v_add_f32_e32 v13, v9, v12
	v_sub_f32_e32 v14, v13, v9
	v_sub_f32_e32 v15, v13, v14
	v_sub_f32_e32 v11, v16, v11
	v_sub_f32_e32 v9, v9, v15
	v_sub_f32_e32 v12, v12, v14
	v_add_f32_e32 v9, v12, v9
	v_add_f32_e32 v12, v11, v8
	v_sub_f32_e32 v14, v12, v11
	v_sub_f32_e32 v15, v12, v14
	v_sub_f32_e32 v11, v11, v15
	v_sub_f32_e32 v8, v8, v14
	v_add_f32_e32 v9, v12, v9
	v_add_f32_e32 v8, v8, v11
	v_add_f32_e32 v11, v13, v9
	v_sub_f32_e32 v12, v11, v13
	v_sub_f32_e32 v9, v9, v12
	v_add_f32_e32 v8, v8, v9
	v_add_f32_e32 v8, v11, v8
	s_mov_b32 s17, 0x33800000
	v_cndmask_b32_e32 v8, v207, v8, vcc
	v_cmp_lt_f32_e64 vcc, |v2|, s17
	v_add_f32_e32 v0, 1.0, v0
	s_nop 0
	v_cndmask_b32_e32 v2, v8, v2, vcc
	s_waitcnt vmcnt(0)
	v_mul_f32_e32 v8, 0x3fb8aa3b, v3
	v_add_f32_e32 v2, v10, v2
	v_fma_f32 v9, v3, s86, -v8
	v_rndne_f32_e32 v10, v8
	v_fmac_f32_e32 v9, 0x32a5705f, v3
	v_sub_f32_e32 v8, v8, v10
	v_add_f32_e32 v8, v8, v9
	v_exp_f32_e32 v8, v8
	v_cvt_i32_f32_e32 v9, v10
	v_cmp_ngt_f32_e32 vcc, s87, v3
	v_add_u32_e32 v10, -1, v154
	v_ldexp_f32 v8, v8, v9
	v_cndmask_b32_e32 v8, 0, v8, vcc
	v_cmp_nlt_f32_e32 vcc, s88, v3
	v_and_b32_e32 v3, 64, v154
	s_nop 0
	v_cndmask_b32_e32 v8, v207, v8, vcc
	v_cmp_lt_i32_e32 vcc, v10, v3
	v_mul_f32_e64 v9, v2, -v8
	s_nop 0
	v_cndmask_b32_e32 v10, v10, v154, vcc
	v_lshlrev_b32_e32 v10, 2, v10
	ds_bpermute_b32 v10, v10, v9
	s_waitcnt lgkmcnt(0)
	v_fma_f32 v2, v2, -v8, v10
	v_add_u32_e32 v8, -2, v154
	v_cmp_lt_i32_e32 vcc, v8, v3
	v_cndmask_b32_e64 v2, v2, v9, s[66:67]
	s_nop 0
	v_cndmask_b32_e32 v8, v8, v154, vcc
	v_lshlrev_b32_e32 v8, 2, v8
	ds_bpermute_b32 v8, v8, v2
	s_waitcnt lgkmcnt(0)
	v_add_f32_e32 v8, v2, v8
	v_cndmask_b32_e64 v2, v8, v2, s[12:13]
	v_add_u32_e32 v8, -4, v154
	v_cmp_lt_i32_e32 vcc, v8, v3
	v_readlane_b32 s12, v252, 36
	v_readlane_b32 s13, v252, 37
	v_cndmask_b32_e32 v8, v8, v154, vcc
	v_lshlrev_b32_e32 v8, 2, v8
	ds_bpermute_b32 v8, v8, v2
	s_waitcnt lgkmcnt(0)
	v_add_f32_e32 v8, v2, v8
	v_cndmask_b32_e64 v2, v8, v2, s[12:13]
	v_add_u32_e32 v8, -8, v154
	v_cmp_lt_i32_e32 vcc, v8, v3
	v_readlane_b32 s12, v252, 38
	v_readlane_b32 s13, v252, 39
	v_cndmask_b32_e32 v8, v8, v154, vcc
	v_lshlrev_b32_e32 v8, 2, v8
	ds_bpermute_b32 v8, v8, v2
	s_waitcnt lgkmcnt(0)
	v_add_f32_e32 v8, v2, v8
	v_cndmask_b32_e64 v2, v8, v2, s[12:13]
	v_add_u32_e32 v8, -16, v154
	v_cmp_lt_i32_e32 vcc, v8, v3
	v_readlane_b32 s12, v252, 40
	v_readlane_b32 s13, v252, 41
	v_cndmask_b32_e32 v8, v8, v154, vcc
	v_lshlrev_b32_e32 v8, 2, v8
	ds_bpermute_b32 v8, v8, v2
	s_waitcnt lgkmcnt(0)
	v_add_f32_e32 v8, v2, v8
	v_cndmask_b32_e64 v2, v8, v2, s[12:13]
	v_subrev_u32_e32 v8, 32, v154
	v_cmp_lt_i32_e32 vcc, v8, v3
	s_nop 1
	v_cndmask_b32_e32 v3, v8, v154, vcc
	v_lshlrev_b32_e32 v3, 2, v3
	ds_bpermute_b32 v3, v3, v2
	s_waitcnt lgkmcnt(0)
	v_add_f32_e32 v3, v2, v3
	v_cndmask_b32_e64 v2, v3, v2, s[4:5]
	v_div_scale_f32 v3, s[92:93], v0, v0, 1.0
	v_rcp_f32_e32 v8, v3
	s_nop 0
	v_fma_f32 v9, -v3, v8, 1.0
	v_fmac_f32_e32 v8, v9, v8
	v_div_scale_f32 v9, vcc, 1.0, v0, 1.0
	v_mul_f32_e32 v10, v9, v8
	v_fma_f32 v11, -v3, v10, v9
	v_fmac_f32_e32 v10, v11, v8
	v_fma_f32 v3, -v3, v10, v9
	v_div_fmas_f32 v3, v3, v8, v10
	v_div_fixup_f32 v0, v3, v0, 1.0
	ds_write2st64_b32 v140, v2, v0 offset0:192 offset1:193
	v_mul_f32_e32 v0, 0x3fb8aa3b, v2
	v_fma_f32 v3, v2, s86, -v0
	v_rndne_f32_e32 v8, v0
	v_fmac_f32_e32 v3, 0x32a5705f, v2
	v_sub_f32_e32 v0, v0, v8
	v_add_f32_e32 v0, v0, v3
	v_exp_f32_e32 v0, v0
	v_cvt_i32_f32_e32 v3, v8
	v_cmp_ngt_f32_e32 vcc, s87, v2
	v_ldexp_f32 v0, v0, v3
	s_nop 0
	v_cndmask_b32_e32 v0, 0, v0, vcc
	v_cmp_nlt_f32_e32 vcc, s88, v2
	s_nop 1
	v_cndmask_b32_e32 v0, v207, v0, vcc
	ds_write_b32 v140, v0 offset:49664

.LBB0_317:
	s_setprio 0
	s_mov_b32 s26, 0
	s_mov_b64 s[18:19], 0
	v_mov_b32_e32 v0, v193
	s_branch .LBB0_319

.LBB0_467:
	s_setprio 0
	s_waitcnt vmcnt(0)
	s_waitcnt vmcnt(63) expcnt(7) lgkmcnt(15)
	s_barrier
	s_and_saveexec_b64 s[0:1], s[96:97]
	v_readlane_b32 s40, v251, 8
	v_readlane_b32 s41, v251, 9
	v_readlane_b32 s42, v251, 10
	v_readlane_b32 s43, v251, 11
	v_readlane_b32 s44, v251, 12
	v_readlane_b32 s45, v251, 13
	v_readlane_b32 s46, v251, 14
	v_readlane_b32 s47, v251, 15
	v_readlane_b32 s48, v251, 16
	v_readlane_b32 s49, v251, 17
	v_readlane_b32 s50, v251, 18
	v_readlane_b32 s51, v251, 19
	v_readlane_b32 s54, v251, 22
	v_readlane_b32 s55, v251, 23
	s_mov_b32 s90, s59
	s_mov_b32 s84, s62
	v_readlane_b32 s62, v252, 29
	s_mov_b64 s[86:87], s[66:67]
	v_readlane_b32 s52, v251, 20
	v_readlane_b32 s53, v251, 21
	s_cbranch_execz .LBB0_519
	v_mov_b32_e32 v0, 0x10800
	s_waitcnt vmcnt(0) expcnt(0) lgkmcnt(0)
	ds_read_b32 v2, v0
	v_mov_b32_e32 v0, 0x10804
	ds_read_b32 v0, v0
	s_waitcnt lgkmcnt(1)
	v_cmp_ne_u32_e32 vcc, 0, v2
	s_cbranch_vccnz .LBB0_483
	v_readlane_b32 s8, v252, 24
	v_readlane_b32 s9, v252, 25
	s_load_dwordx2 s[4:5], s[8:9], 0x4
	s_add_u32 s8, s44, 0x1000
	s_addc_u32 s9, s45, 0
	s_add_u32 s10, s44, 0x1100
	s_addc_u32 s11, s45, 0
	s_add_u32 s14, s44, 0x1200
	s_addc_u32 s15, s45, 0
	s_waitcnt lgkmcnt(0)
	s_mul_i32 s3, s4, s33
	s_add_u32 s16, s44, 0x1300
	s_mul_i32 s3, s3, s5
	s_addc_u32 s17, s45, 0
	s_mov_b32 s4, 1
	v_mov_b32_e32 v16, 0
	s_branch .LBB0_471
